# grid barrier: XCD leader publishes the generation word before its own L1 invalidate (buffer_inv moved after the XGEN atomic)
# baseline (speedup 1.0000x reference)
; __device__ __forceinline__ unsigned xb_ld(unsigned* p)              { return __hip_atomic_load(p, __ATOMIC_RELAXED, __HIP_MEMORY_SCOPE_AGENT); }
; __device__ __forceinline__ unsigned xb_add(unsigned* p, unsigned v) { return __hip_atomic_fetch_add(p, v, __ATOMIC_RELAXED, __HIP_MEMORY_SCOPE_AGENT); }
; #define XB_SPIN(cond, bar) do { unsigned _sp = 0; while (cond) { __builtin_amdgcn_s_sleep(1); \
;     if ((++_sp & 255u) == 0u) { if (xb_ld(&(bar)[XB_TMO])) break; if (_sp > XB_SPIN_CAP) { atomicAdd(&(bar)[XB_TMO], 1u); break; } } } } while (0)
; __device__ __forceinline__ void xcd_barrier(const XcdBarrier& b) {
;     ...
;             if (og + 1u == (tg + 1u) * nx) xb_add(&bar[XB_TOPGEN], 1u);
;             else XB_SPIN(xb_ld(&bar[XB_TOPGEN]) == tg, bar);
;             __builtin_amdgcn_fence(__ATOMIC_ACQUIRE, "agent");
;             xb_add(&bar[XB_XGEN(b.x)], 1u);
;             asm volatile("s_waitcnt vmcnt(0)" ::: "memory");
.LBB0_85:
	s_or_b64 exec, exec, s[8:9]
	s_mov_b64 s[8:9], exec
	v_mbcnt_lo_u32_b32 v2, s8, 0
	v_mbcnt_hi_u32_b32 v2, s9, v2
	v_cmp_eq_u32_e32 vcc, 0, v2
	s_waitcnt vmcnt(0)
	s_and_saveexec_b64 s[12:13], vcc
	s_cbranch_execz .LBB0_87
	s_bcnt1_i32_b64 s8, s[8:9]
	v_mov_b32_e32 v2, s8
	global_atomic_add v231, v2, s[10:11] offset:1024
.LBB0_87:
	s_or_b64 exec, exec, s[12:13]
	buffer_inv sc1
	s_waitcnt vmcnt(0)

; __device__ __forceinline__ unsigned xb_ld(unsigned* p)              { return __hip_atomic_load(p, __ATOMIC_RELAXED, __HIP_MEMORY_SCOPE_AGENT); }
; __device__ __forceinline__ unsigned xb_add(unsigned* p, unsigned v) { return __hip_atomic_fetch_add(p, v, __ATOMIC_RELAXED, __HIP_MEMORY_SCOPE_AGENT); }
; #define XB_SPIN(cond, bar) do { unsigned _sp = 0; while (cond) { __builtin_amdgcn_s_sleep(1); \
;     if ((++_sp & 255u) == 0u) { if (xb_ld(&(bar)[XB_TMO])) break; if (_sp > XB_SPIN_CAP) { atomicAdd(&(bar)[XB_TMO], 1u); break; } } } } while (0)
; __device__ __forceinline__ void xcd_barrier(const XcdBarrier& b) {
;     ...
;             if (og + 1u == (tg + 1u) * nx) xb_add(&bar[XB_TOPGEN], 1u);
;             else XB_SPIN(xb_ld(&bar[XB_TOPGEN]) == tg, bar);
;             __builtin_amdgcn_fence(__ATOMIC_ACQUIRE, "agent");
;             xb_add(&bar[XB_XGEN(b.x)], 1u);
;             asm volatile("s_waitcnt vmcnt(0)" ::: "memory");
.LBB0_1512:
	s_or_b64 exec, exec, s[10:11]
	s_mov_b64 s[10:11], exec
	v_mbcnt_lo_u32_b32 v2, s10, 0
	v_mbcnt_hi_u32_b32 v2, s11, v2
	v_cmp_eq_u32_e32 vcc, 0, v2
	s_waitcnt vmcnt(0)
	s_and_saveexec_b64 s[14:15], vcc
	s_cbranch_execz .LBB0_1514
	s_bcnt1_i32_b64 s10, s[10:11]
	v_mov_b32_e32 v2, s10
	global_atomic_add v231, v2, s[12:13] offset:1024
.LBB0_1514:
	s_or_b64 exec, exec, s[14:15]
	buffer_inv sc1
	s_waitcnt vmcnt(0)

; __device__ __forceinline__ unsigned xb_ld(unsigned* p)              { return __hip_atomic_load(p, __ATOMIC_RELAXED, __HIP_MEMORY_SCOPE_AGENT); }
; __device__ __forceinline__ unsigned xb_add(unsigned* p, unsigned v) { return __hip_atomic_fetch_add(p, v, __ATOMIC_RELAXED, __HIP_MEMORY_SCOPE_AGENT); }
; #define XB_SPIN(cond, bar) do { unsigned _sp = 0; while (cond) { __builtin_amdgcn_s_sleep(1); \
;     if ((++_sp & 255u) == 0u) { if (xb_ld(&(bar)[XB_TMO])) break; if (_sp > XB_SPIN_CAP) { atomicAdd(&(bar)[XB_TMO], 1u); break; } } } } while (0)
; __device__ __forceinline__ void xcd_barrier(const XcdBarrier& b) {
;     ...
;             if (og + 1u == (tg + 1u) * nx) xb_add(&bar[XB_TOPGEN], 1u);
;             else XB_SPIN(xb_ld(&bar[XB_TOPGEN]) == tg, bar);
;             __builtin_amdgcn_fence(__ATOMIC_ACQUIRE, "agent");
;             xb_add(&bar[XB_XGEN(b.x)], 1u);
;             asm volatile("s_waitcnt vmcnt(0)" ::: "memory");
.LBB0_1579:
	s_or_b64 exec, exec, s[12:13]
	s_mov_b64 s[12:13], exec
	v_mbcnt_lo_u32_b32 v2, s12, 0
	v_mbcnt_hi_u32_b32 v2, s13, v2
	v_cmp_eq_u32_e32 vcc, 0, v2
	s_waitcnt vmcnt(0)
	s_and_saveexec_b64 s[16:17], vcc
	s_cbranch_execz .LBB0_1581
	s_bcnt1_i32_b64 s12, s[12:13]
	v_mov_b32_e32 v2, s12
	global_atomic_add v231, v2, s[14:15] offset:1024
.LBB0_1581:
	s_or_b64 exec, exec, s[16:17]
	buffer_inv sc1
	s_waitcnt vmcnt(0)
